# speedup vs baseline: 1.0074x; 1.0074x over previous
; DEV void phase_moe2(const Params& p, int l, unsigned char* smem) {
;     ...
;   moe_prefix(p, l, 8, smem, s_cnt, s_off, s_tile);
;   const int ntile = s_tile[32];
;   for (int t = blockIdx.x; t < ntile; t += gridDim.x) {
.LBB0_714:
	s_or_b64 exec, exec, s[4:5]
	s_waitcnt lgkmcnt(0)
	s_barrier
	ds_read_b32 v88, v69 offset:33152
	s_mov_b32 s18, s88
	s_waitcnt lgkmcnt(0)
	s_and_b32 s0, s33, 7
	s_cmp_lg_u32 s0, 0
	s_cbranch_scc1 .Lremap_done_m2l0
	v_readfirstlane_b32 s0, v88
	s_lshr_b32 s0, s0, 3
	s_and_b32 s1, s88, 7
	s_mul_i32 s4, s1, s0
	s_lshr_b32 s5, s88, 3
	s_and_b32 s1, s5, 31
	s_mul_i32 s1, s1, 3
	s_lshr_b32 s10, s5, 5
	s_add_i32 s1, s1, s10
	s_cmpk_eq_u32 s33, 0x300
	s_cselect_b32 s5, s1, s5
	s_add_i32 s18, s4, s5
	s_add_i32 s4, s4, s0
	v_mov_b32_e32 v88, s4
.Lremap_done_m2l0:
	v_cmp_ge_i32_e32 vcc, s18, v88
	s_cbranch_vccz .LBB0_716
	s_branch .LBB0_706
.LBB0_715:
	s_or_b64 exec, exec, s[4:5]
	s_lshr_b32 s4, s33, 3
	s_and_b32 s5, s33, 7
	s_cmp_eq_u32 s5, 0
	s_cselect_b32 s4, s4, s33
	s_add_i32 s18, s18, s4
	v_cmp_lt_i32_e32 vcc, s18, v88
	s_barrier
	s_cbranch_vccz .LBB0_706

; DEV void phase_moe2(const Params& p, int l, unsigned char* smem) {
;     ...
;   moe_prefix(p, l, 8, smem, s_cnt, s_off, s_tile);
;   const int ntile = s_tile[32];
;   for (int t = blockIdx.x; t < ntile; t += gridDim.x) {
.LBB0_2406:
	s_or_b64 exec, exec, s[4:5]
	s_waitcnt lgkmcnt(0)
	s_barrier
	ds_read_b32 v88, v69 offset:33152
	s_mov_b32 s22, s31
	s_waitcnt lgkmcnt(0)
	s_and_b32 s0, s33, 7
	s_cmp_lg_u32 s0, 0
	s_cbranch_scc1 .Lremap_done_m2l1
	v_readfirstlane_b32 s0, v88
	s_lshr_b32 s0, s0, 3
	s_and_b32 s1, s31, 7
	s_mul_i32 s4, s1, s0
	s_lshr_b32 s5, s31, 3
	s_and_b32 s1, s5, 31
	s_mul_i32 s1, s1, 3
	s_lshr_b32 s8, s5, 5
	s_add_i32 s1, s1, s8
	s_cmpk_eq_u32 s33, 0x300
	s_cselect_b32 s5, s1, s5
	s_add_i32 s22, s4, s5
	s_add_i32 s4, s4, s0
	v_mov_b32_e32 v88, s4
.Lremap_done_m2l1:
	v_cmp_ge_i32_e32 vcc, s22, v88
	s_cbranch_vccz .LBB0_2408
	s_branch .LBB0_2398
.LBB0_2407:
	s_or_b64 exec, exec, s[0:1]
	s_lshr_b32 s4, s33, 3
	s_and_b32 s5, s33, 7
	s_cmp_eq_u32 s5, 0
	s_cselect_b32 s4, s4, s33
	s_add_i32 s22, s22, s4
	v_cmp_lt_i32_e32 vcc, s22, v88
	s_barrier
	s_cbranch_vccz .LBB0_2398
